# NSA selected loop: the sely any-lane test uses the compare mask directly (cndmask + compare + scalar compare replaced by one scalar and)
# baseline (speedup 1.0000x reference)
.LBB0_352:
	v_cmp_le_i32_e32 vcc, s68, v123
	s_and_saveexec_b64 s[40:41], vcc
	s_cbranch_execz .LBB0_370
	s_lshr_b32 s2, s68, 6
	s_cmpk_lt_u32 s68, 0x1000
	s_cselect_b64 vcc, -1, 0
	s_sub_i32 s3, s2, 64
	s_and_b64 s[0:1], vcc, exec
	s_cselect_b32 s0, 1, 0xffffffc1
	v_cndmask_b32_e32 v35, v117, v119, vcc
	v_cndmask_b32_e32 v34, v128, v130, vcc
	s_cselect_b32 s1, s2, s3
	s_add_i32 s0, s0, s2
	v_lshrrev_b64 v[36:37], s1, v[34:35]
	v_lshrrev_b64 v[34:35], s0, v[34:35]
	v_and_b32_e32 v1, 1, v36
	v_and_b32_e32 v34, 1, v34
	s_add_i32 s2, s68, 61
	v_cmp_eq_u32_e32 vcc, 1, v1
	v_cmp_eq_u32_e64 s[50:51], 1, v34
	v_cmp_ne_u32_e64 s[0:1], 0, v1
	v_cmp_le_i32_e64 s[2:3], s2, v176
	s_mov_b64 s[4:5], 0
	s_and_saveexec_b64 s[6:7], s[2:3]
	s_and_b64 s[2:3], s[50:51], exec
	s_cselect_b64 s[2:3], -1, 0
	s_and_b64 s[4:5], s[2:3], exec
	s_or_b64 exec, exec, s[6:7]
	s_cmp_lg_u64 s[0:1], 0
	s_cselect_b64 s[0:1], -1, 0
	s_bitcmp1_b32 s8, 0
	s_cselect_b32 s2, 0x9000, 0
	s_add_i32 s90, s2, 0
	s_and_b64 s[2:3], s[0:1], s[4:5]
	s_xor_b64 s[2:3], s[2:3], -1
	s_and_saveexec_b64 s[6:7], s[2:3]
	s_xor_b64 s[62:63], exec, s[6:7]
	s_cbranch_execz .LBB0_363
	s_or_b64 s[2:3], s[0:1], s[4:5]
	s_and_saveexec_b64 s[64:65], s[2:3]
	s_cbranch_execz .LBB0_362
	s_and_b64 s[2:3], s[0:1], exec
	s_cselect_b32 s2, 0, 64
	v_cndmask_b32_e64 v1, 0, 1, vcc
	v_cndmask_b32_e64 v34, 0, 1, s[50:51]
	v_cndmask_b32_e64 v1, v34, v1, s[0:1]
	s_mul_i32 s3, s2, 0x90
	v_and_b32_e32 v1, 1, v1
	s_add_i32 s70, s90, s3
	v_cmp_eq_u32_e64 s[0:1], 1, v1
	v_readfirstlane_b32 s4, v176
	s_add_i32 s3, s2, s68
	s_add_i32 s3, s3, 63
	s_cmp_le_i32 s3, s4
	s_cbranch_scc0 .Lnsa_single_slow
	v_add3_u32 v1, s70, v151, v152
	v_add3_u32 v179, s70, v154, v155
	ds_read_b128 v[180:183], v1
	ds_read_b128 v[184:187], v1 offset:4608
	ds_read_b128 v[188:191], v1 offset:32
	ds_read_b128 v[192:195], v1 offset:4640
	ds_read_b128 v[196:199], v1 offset:64
	ds_read_b128 v[200:203], v1 offset:4672
	ds_read_b128 v[204:207], v1 offset:96
	ds_read_b128 v[208:211], v1 offset:4704
	v_mov_b32_e32 v220, s87
	v_cndmask_b32_e64 v142, v234, -v220, s[0:1]
	v_mov_b32_e32 v168, 0x3e38aa3b
	s_waitcnt lgkmcnt(6)
	v_mfma_f32_32x32x16_bf16 v[34:49], v[180:183], v[98:101], 0
	v_mfma_f32_32x32x16_bf16 v[50:65], v[184:187], v[98:101], 0
	s_waitcnt lgkmcnt(4)
	v_mfma_f32_32x32x16_bf16 v[34:49], v[188:191], v[102:105], v[34:49]
	v_mfma_f32_32x32x16_bf16 v[50:65], v[192:195], v[102:105], v[50:65]
	s_waitcnt lgkmcnt(2)
	v_mfma_f32_32x32x16_bf16 v[34:49], v[196:199], v[106:109], v[34:49]
	v_mfma_f32_32x32x16_bf16 v[50:65], v[200:203], v[106:109], v[50:65]
	s_waitcnt lgkmcnt(0)
	v_mfma_f32_32x32x16_bf16 v[34:49], v[204:207], v[110:113], v[34:49]
	v_mfma_f32_32x32x16_bf16 v[50:65], v[208:211], v[110:113], v[50:65]
	ds_read_b64_tr_b16 v[212:213], v179 offset:18432
	ds_read_b64_tr_b16 v[214:215], v179 offset:19584
	ds_read_b64_tr_b16 v[216:217], v179 offset:18496
	ds_read_b64_tr_b16 v[218:219], v179 offset:19648
	ds_read_b64_tr_b16 v[236:237], v179 offset:20736
	ds_read_b64_tr_b16 v[238:239], v179 offset:21888
	ds_read_b64_tr_b16 v[240:241], v179 offset:20800
	ds_read_b64_tr_b16 v[242:243], v179 offset:21952
	ds_read_b64_tr_b16 v[244:245], v179 offset:23040
	ds_read_b64_tr_b16 v[246:247], v179 offset:24192
	v_mov_b64_e32 v[220:221], 0
	s_nop 7
	v_pk_fma_f32 v[34:35], v[34:35], v[168:169], v[142:143] op_sel_hi:[1,0,0]
	v_pk_fma_f32 v[36:37], v[36:37], v[168:169], v[142:143] op_sel_hi:[1,0,0]
	v_pk_fma_f32 v[38:39], v[38:39], v[168:169], v[142:143] op_sel_hi:[1,0,0]
	v_pk_fma_f32 v[40:41], v[40:41], v[168:169], v[142:143] op_sel_hi:[1,0,0]
	v_pk_fma_f32 v[42:43], v[42:43], v[168:169], v[142:143] op_sel_hi:[1,0,0]
	v_pk_fma_f32 v[44:45], v[44:45], v[168:169], v[142:143] op_sel_hi:[1,0,0]
	v_pk_fma_f32 v[46:47], v[46:47], v[168:169], v[142:143] op_sel_hi:[1,0,0]
	v_pk_fma_f32 v[48:49], v[48:49], v[168:169], v[142:143] op_sel_hi:[1,0,0]
	v_exp_f32_e32 v34, v34
	v_exp_f32_e32 v35, v35
	v_exp_f32_e32 v36, v36
	v_exp_f32_e32 v37, v37
	v_exp_f32_e32 v38, v38
	v_exp_f32_e32 v39, v39
	v_exp_f32_e32 v40, v40
	v_exp_f32_e32 v41, v41
	v_exp_f32_e32 v42, v42
	v_exp_f32_e32 v43, v43
	v_exp_f32_e32 v44, v44
	v_exp_f32_e32 v45, v45
	v_exp_f32_e32 v46, v46
	v_exp_f32_e32 v47, v47
	v_exp_f32_e32 v48, v48
	v_exp_f32_e32 v49, v49
	v_pk_fma_f32 v[50:51], v[50:51], v[168:169], v[142:143] op_sel_hi:[1,0,0]
	v_pk_fma_f32 v[52:53], v[52:53], v[168:169], v[142:143] op_sel_hi:[1,0,0]
	v_pk_fma_f32 v[54:55], v[54:55], v[168:169], v[142:143] op_sel_hi:[1,0,0]
	v_pk_fma_f32 v[56:57], v[56:57], v[168:169], v[142:143] op_sel_hi:[1,0,0]
	v_pk_fma_f32 v[58:59], v[58:59], v[168:169], v[142:143] op_sel_hi:[1,0,0]
	v_pk_fma_f32 v[60:61], v[60:61], v[168:169], v[142:143] op_sel_hi:[1,0,0]
	v_pk_fma_f32 v[62:63], v[62:63], v[168:169], v[142:143] op_sel_hi:[1,0,0]
	v_pk_fma_f32 v[64:65], v[64:65], v[168:169], v[142:143] op_sel_hi:[1,0,0]
	v_exp_f32_e32 v50, v50
	v_exp_f32_e32 v51, v51
	v_exp_f32_e32 v52, v52
	v_exp_f32_e32 v53, v53
	v_exp_f32_e32 v54, v54
	v_exp_f32_e32 v55, v55
	v_exp_f32_e32 v56, v56
	v_exp_f32_e32 v57, v57
	v_exp_f32_e32 v58, v58
	v_exp_f32_e32 v59, v59
	v_exp_f32_e32 v60, v60
	v_exp_f32_e32 v61, v61
	v_exp_f32_e32 v62, v62
	v_exp_f32_e32 v63, v63
	v_exp_f32_e32 v64, v64
	v_exp_f32_e32 v65, v65
	v_pk_add_f32 v[220:221], v[34:35], v[220:221]
	v_pk_add_f32 v[220:221], v[36:37], v[220:221]
	v_pk_add_f32 v[220:221], v[38:39], v[220:221]
	v_pk_add_f32 v[220:221], v[40:41], v[220:221]
	v_pk_add_f32 v[220:221], v[42:43], v[220:221]
	v_pk_add_f32 v[220:221], v[44:45], v[220:221]
	v_pk_add_f32 v[220:221], v[46:47], v[220:221]
	v_pk_add_f32 v[220:221], v[48:49], v[220:221]
	v_cvt_pk_bf16_f32 v34, v34, v35
	v_cvt_pk_bf16_f32 v35, v36, v37
	v_cvt_pk_bf16_f32 v36, v38, v39
	v_cvt_pk_bf16_f32 v37, v40, v41
	v_cvt_pk_bf16_f32 v42, v42, v43
	v_cvt_pk_bf16_f32 v43, v44, v45
	v_cvt_pk_bf16_f32 v44, v46, v47
	v_cvt_pk_bf16_f32 v45, v48, v49
	v_pk_add_f32 v[220:221], v[50:51], v[220:221]
	v_pk_add_f32 v[220:221], v[52:53], v[220:221]
	v_pk_add_f32 v[220:221], v[54:55], v[220:221]
	v_pk_add_f32 v[220:221], v[56:57], v[220:221]
	v_pk_add_f32 v[220:221], v[58:59], v[220:221]
	v_pk_add_f32 v[220:221], v[60:61], v[220:221]
	v_pk_add_f32 v[220:221], v[62:63], v[220:221]
	v_pk_add_f32 v[220:221], v[64:65], v[220:221]
	v_cvt_pk_bf16_f32 v50, v50, v51
	v_cvt_pk_bf16_f32 v51, v52, v53
	v_cvt_pk_bf16_f32 v52, v54, v55
	v_cvt_pk_bf16_f32 v53, v56, v57
	v_cvt_pk_bf16_f32 v58, v58, v59
	v_cvt_pk_bf16_f32 v59, v60, v61
	v_cvt_pk_bf16_f32 v60, v62, v63
	v_cvt_pk_bf16_f32 v61, v64, v65
	v_add_f32_e32 v143, v143, v220
	v_add_f32_e32 v143, v143, v221
	s_waitcnt lgkmcnt(8)
	v_mfma_f32_32x32x16_bf16 v[18:33], v[212:215], v[34:37], v[18:33]
	ds_read_b64_tr_b16 v[248:249], v179 offset:23104
	ds_read_b64_tr_b16 v[250:251], v179 offset:24256
	s_waitcnt lgkmcnt(8)
	v_mfma_f32_32x32x16_bf16 v[2:17], v[216:219], v[34:37], v[2:17]
	ds_read_b64_tr_b16 v[212:213], v179 offset:25344
	ds_read_b64_tr_b16 v[214:215], v179 offset:26496
	s_waitcnt lgkmcnt(8)
	v_mfma_f32_32x32x16_bf16 v[18:33], v[236:239], v[42:45], v[18:33]
	ds_read_b64_tr_b16 v[216:217], v179 offset:25408
	ds_read_b64_tr_b16 v[218:219], v179 offset:26560
	s_waitcnt lgkmcnt(8)
	v_mfma_f32_32x32x16_bf16 v[2:17], v[240:243], v[42:45], v[2:17]
	s_waitcnt lgkmcnt(6)
	v_mfma_f32_32x32x16_bf16 v[18:33], v[244:247], v[50:53], v[18:33]
	s_waitcnt lgkmcnt(4)
	v_mfma_f32_32x32x16_bf16 v[2:17], v[248:251], v[50:53], v[2:17]
	s_waitcnt lgkmcnt(2)
	v_mfma_f32_32x32x16_bf16 v[18:33], v[212:215], v[58:61], v[18:33]
	s_waitcnt lgkmcnt(0)
	v_mfma_f32_32x32x16_bf16 v[2:17], v[216:219], v[58:61], v[2:17]
	s_branch .LBB0_362
